# GEMM tile mapping: shift/mask instead of generic division by the group size at 15 sites (6 more than v62)
# baseline (speedup 1.0000x reference)
.LBB0_953:
	s_ashr_i32 s6, s38, 3
	s_add_i32 s6, s41, s6
	s_ashr_i32 s7, s6, 31
	s_lshr_b32 s7, s7, 27
	s_add_i32 s7, s6, s7
	s_ashr_i32 s38, s7, 5
	s_lshl_b32 s40, s38, 3
	s_sub_i32 s38, 64, s40
	s_min_i32 s41, s38, 8
	s_andn2_b32 s7, s7, 31
	s_sub_i32 s6, s6, s7
	s_abs_i32 s7, s6
	s_mul_i32 s39, s39, -3
	s_lshr_b32 s38, s6, 3
	s_and_b32 s6, s6, 7
	s_add_i32 s42, s40, s6
	s_add_i32 s40, s39, s66

.LBB0_1630:
	s_ashr_i32 s10, s16, 3
	s_add_i32 s10, s53, s10
	s_ashr_i32 s11, s10, 31
	s_lshr_b32 s11, s11, 27
	s_add_i32 s11, s10, s11
	s_ashr_i32 s16, s11, 5
	s_lshl_b32 s16, s16, 3
	s_sub_i32 s52, 64, s16
	s_min_i32 s52, s52, 8
	s_andn2_b32 s11, s11, 31
	s_sub_i32 s10, s10, s11
	s_abs_i32 s11, s10
	s_nop 0
	s_lshr_b32 s89, s10, 3
	s_and_b32 s10, s10, 7
	s_add_i32 s90, s16, s10

.LBB0_2186:
	s_add_i32 s22, s71, 1
	s_lshl_b64 s[4:5], s[22:23], 8
	s_add_u32 s64, s4, s95
	s_addc_u32 s65, s5, s9
	v_cmp_gt_i64_e32 vcc, s[64:65], v[148:149]
	v_cmp_lt_i64_e64 s[4:5], s[64:65], v[146:147]
	s_cbranch_vccnz .LBB0_2188
	s_ashr_i32 s1, s64, 31
	s_lshr_b32 s1, s1, 29
	s_add_i32 s1, s64, s1
	s_ashr_i32 s7, s1, 3
	s_and_b32 s1, s1, -8
	s_sub_i32 s1, s64, s1
	s_cmp_lt_i32 s1, 0
	s_cselect_b32 s60, s33, 0x58
	s_mul_i32 s1, s60, s1
	s_add_i32 s1, s1, s7
	s_mul_hi_i32 s7, s1, 0x2e8ba2e9
	s_lshr_b32 s60, s7, 31
	s_ashr_i32 s7, s7, 4
	s_add_i32 s7, s7, s60
	s_lshl_b32 s61, s7, 3
	s_sub_i32 s60, 64, s61
	s_min_i32 s62, s60, 8
	s_mulk_i32 s7, 0x58
	s_sub_i32 s1, s1, s7
	s_abs_i32 s7, s1
	s_nop 0
	s_lshr_b32 s60, s1, 3
	s_and_b32 s1, s1, 7
	s_add_i32 s62, s1, s61

.LBB0_3013:
	s_ashr_i32 s6, s38, 3
	s_add_i32 s6, s41, s6
	s_ashr_i32 s7, s6, 31
	s_lshr_b32 s7, s7, 27
	s_add_i32 s7, s6, s7
	s_ashr_i32 s38, s7, 5
	s_lshl_b32 s40, s38, 3
	s_sub_i32 s38, 64, s40
	s_min_i32 s41, s38, 8
	s_andn2_b32 s7, s7, 31
	s_sub_i32 s6, s6, s7
	s_abs_i32 s7, s6
	s_mul_i32 s39, s39, -3
	s_lshr_b32 s38, s6, 3
	s_and_b32 s6, s6, 7
	s_add_i32 s42, s40, s6
	s_add_i32 s40, s39, s68

.LBB0_3530:
	s_andn2_b64 vcc, exec, s[40:41]
	s_cbranch_vccnz .LBB0_3534
	v_cmp_gt_i64_e32 vcc, s[0:1], v[196:197]
	s_mov_b64 s[42:43], 0
	s_cbranch_vccnz .LBB0_3533
	s_ashr_i32 s1, s0, 31
	s_lshr_b32 s1, s1, 29
	s_add_i32 s1, s0, s1
	s_ashr_i32 s36, s1, 3
	s_and_b32 s1, s1, -8
	s_sub_i32 s0, s0, s1
	s_cmp_lt_i32 s0, 0
	s_cselect_b32 s1, s62, 0xb0
	s_mul_i32 s0, s1, s0
	s_add_i32 s0, s0, s36
	s_mul_hi_i32 s1, s0, 0x2e8ba2e9
	s_lshr_b32 s36, s1, 31
	s_ashr_i32 s1, s1, 5
	s_add_i32 s1, s1, s36
	s_lshl_b32 s37, s1, 3
	s_sub_i32 s36, 64, s37
	s_min_i32 s38, s36, 8
	s_mulk_i32 s1, 0xb0
	s_sub_i32 s0, s0, s1
	s_abs_i32 s1, s0
	s_mov_b32 s92, 0
	s_lshr_b32 s36, s0, 3
	s_and_b32 s0, s0, 7
	s_add_i32 s38, s0, s37
	s_mov_b64 s[42:43], -1

.LBB0_3688:
	s_ashr_i32 s2, s18, 3
	s_add_i32 s2, s24, s2
	s_ashr_i32 s3, s2, 31
	s_lshr_b32 s3, s3, 27
	s_add_i32 s3, s2, s3
	s_ashr_i32 s18, s3, 5
	s_lshl_b32 s18, s18, 3
	s_sub_i32 s19, 64, s18
	s_min_i32 s19, s19, 8
	s_andn2_b32 s3, s3, 31
	s_sub_i32 s2, s2, s3
	s_abs_i32 s3, s2
	s_nop 0
	s_lshr_b32 s50, s2, 3
	s_and_b32 s2, s2, 7
	s_add_i32 s51, s18, s2
